# barrier: release read off the arrival counters themselves (>= compare): XCD counter on local seams, cross-XCD counter on global seams; no generation words, leader arrives cross-XCD without a ticket
# baseline (speedup 1.0000x reference)
; __device__ __forceinline__ unsigned xb_ld(unsigned* p)              { return __hip_atomic_load(p, __ATOMIC_RELAXED, __HIP_MEMORY_SCOPE_AGENT); }
; __device__ __forceinline__ unsigned xb_add(unsigned* p, unsigned v) { return __hip_atomic_fetch_add(p, v, __ATOMIC_RELAXED, __HIP_MEMORY_SCOPE_AGENT); }
; #define XB_SPIN(cond, bar) do { unsigned _sp = 0; while (cond) { __builtin_amdgcn_s_sleep(1); \
;     if ((++_sp & 255u) == 0u) { if (xb_ld(&(bar)[XB_TMO])) break; if (_sp > XB_SPIN_CAP) { atomicAdd(&(bar)[XB_TMO], 1u); break; } } } } while (0)
; __device__ __forceinline__ void xcd_barrier(const XcdBarrier& b) {
;     ...
;         const unsigned old = xb_add(&bar[XB_XSUB(b.x)], 1u);
;         const unsigned gen = old / nloc;
;         if (old + 1u == (gen + 1u) * nloc) {
;             __builtin_amdgcn_fence(__ATOMIC_RELEASE, "agent");
;             asm volatile("s_waitcnt vmcnt(0)" ::: "memory");
;             const unsigned og = xb_add(&bar[XB_TOP], 1u);
;             const unsigned tg = og / nx;
;             if (og + 1u == (tg + 1u) * nx) xb_add(&bar[XB_TOPGEN], 1u);
;             else XB_SPIN(xb_ld(&bar[XB_TOPGEN]) == tg, bar);
;             __builtin_amdgcn_fence(__ATOMIC_ACQUIRE, "agent");
;             xb_add(&bar[XB_XGEN(b.x)], 1u);
;             asm volatile("s_waitcnt vmcnt(0)" ::: "memory");
;         } else {
;             XB_SPIN(xb_ld(&bar[XB_XGEN(b.x)]) == gen, bar);
.LBB0_380:
	s_or_b64 exec, exec, s[6:7]
	buffer_inv sc1
	v_cvt_f32_u32_e32 v4, v2
	s_waitcnt vmcnt(1)
	v_readfirstlane_b32 s2, v3
	v_sub_u32_e32 v3, 0, v2
	v_rcp_iflag_f32_e32 v4, v4
	v_add_u32_e32 v5, s2, v1
	v_mul_f32_e32 v4, 0x4f7ffffe, v4
	v_cvt_u32_f32_e32 v4, v4
	v_mul_lo_u32 v1, v3, v4
	v_mul_hi_u32 v1, v4, v1
	v_add_u32_e32 v1, v4, v1
	v_mul_hi_u32 v1, v5, v1
	v_mul_lo_u32 v3, v1, v2
	v_sub_u32_e32 v3, v5, v3
	v_add_u32_e32 v4, 1, v1
	v_cmp_ge_u32_e32 vcc, v3, v2
	s_nop 1
	v_cndmask_b32_e32 v1, v1, v4, vcc
	v_sub_u32_e32 v4, v3, v2
	v_cndmask_b32_e32 v3, v3, v4, vcc
	v_add_u32_e32 v4, 1, v1
	v_cmp_ge_u32_e32 vcc, v3, v2
	v_add_u32_e32 v3, 1, v5
	s_nop 0
	v_cndmask_b32_e32 v1, v1, v4, vcc
	v_mul_lo_u32 v4, v2, v1
	v_add_u32_e32 v2, v4, v2
	v_cmp_ne_u32_e32 vcc, v3, v2
	s_and_saveexec_b64 s[6:7], vcc
	s_xor_b64 s[6:7], exec, s[6:7]
	s_cbranch_execz .LBB0_394
	s_waitcnt lgkmcnt(0)
	s_cmp_lt_i32 s100, 0
	s_cbranch_scc1 .Ltg_poll_local
	v_readlane_b32 s20, v253, 24
	v_readlane_b32 s21, v253, 25
	s_add_i32 s2, s100, 1
	v_mul_lo_u32 v1, v0, s2
	s_branch .Ltg_poll_go
.Ltg_poll_local:
	v_readlane_b32 s20, v253, 20
	v_readlane_b32 s21, v253, 21
	v_mov_b32_e32 v1, v2
.Ltg_poll_go:
	s_nop 4
	global_load_dword v0, v193, s[20:21] sc1
	s_waitcnt vmcnt(0)
	v_cmp_lt_u32_e32 vcc, v0, v1
	s_and_saveexec_b64 s[8:9], vcc
	s_cbranch_execz .LBB0_393
	s_mov_b32 s2, 1
	s_mov_b64 s[10:11], 0
	s_branch .LBB0_384

; __device__ __forceinline__ unsigned xb_ld(unsigned* p)              { return __hip_atomic_load(p, __ATOMIC_RELAXED, __HIP_MEMORY_SCOPE_AGENT); }
; #define XB_SPIN(cond, bar) do { unsigned _sp = 0; while (cond) { __builtin_amdgcn_s_sleep(1); \
;     if ((++_sp & 255u) == 0u) { if (xb_ld(&(bar)[XB_TMO])) break; if (_sp > XB_SPIN_CAP) { atomicAdd(&(bar)[XB_TMO], 1u); break; } } } } while (0)
; __device__ __forceinline__ void xcd_barrier(const XcdBarrier& b) {
;     ...
;             XB_SPIN(xb_ld(&bar[XB_XGEN(b.x)]) == gen, bar);
.LBB0_388:
	s_mov_b64 s[14:15], s[20:21]
	s_add_i32 s2, s2, 1
	s_mov_b64 s[16:17], -1
	s_nop 2
	global_load_dword v0, v193, s[14:15] sc1
	s_waitcnt vmcnt(0)
	v_cmp_ge_u32_e32 vcc, v0, v1
	s_orn2_b64 s[14:15], vcc, exec
	s_branch .LBB0_383

; __device__ __forceinline__ unsigned xb_ld(unsigned* p)              { return __hip_atomic_load(p, __ATOMIC_RELAXED, __HIP_MEMORY_SCOPE_AGENT); }
; __device__ __forceinline__ unsigned xb_add(unsigned* p, unsigned v) { return __hip_atomic_fetch_add(p, v, __ATOMIC_RELAXED, __HIP_MEMORY_SCOPE_AGENT); }
; #define XB_SPIN(cond, bar) do { unsigned _sp = 0; while (cond) { __builtin_amdgcn_s_sleep(1); \
;     if ((++_sp & 255u) == 0u) { if (xb_ld(&(bar)[XB_TMO])) break; if (_sp > XB_SPIN_CAP) { atomicAdd(&(bar)[XB_TMO], 1u); break; } } } } while (0)
; __device__ __forceinline__ void xcd_barrier(const XcdBarrier& b) {
;     ...
;             __builtin_amdgcn_fence(__ATOMIC_RELEASE, "agent");
;             asm volatile("s_waitcnt vmcnt(0)" ::: "memory");
;             const unsigned og = xb_add(&bar[XB_TOP], 1u);
;             const unsigned tg = og / nx;
;             if (og + 1u == (tg + 1u) * nx) xb_add(&bar[XB_TOPGEN], 1u);
;             else XB_SPIN(xb_ld(&bar[XB_TOPGEN]) == tg, bar);
;             __builtin_amdgcn_fence(__ATOMIC_ACQUIRE, "agent");
.Lxl_global:
	buffer_wbl2 sc1
	s_waitcnt lgkmcnt(0)
	s_waitcnt vmcnt(0)
	v_mbcnt_lo_u32_b32 v1, s6, 0
	v_mbcnt_hi_u32_b32 v1, s7, v1
	v_cmp_eq_u32_e32 vcc, 0, v1
	s_and_saveexec_b64 s[8:9], vcc
	s_cbranch_execz .LBB0_397
	s_bcnt1_i32_b64 s2, s[6:7]
	v_readlane_b32 s6, v253, 24
	v_mov_b32_e32 v2, s2
	v_readlane_b32 s7, v253, 25
	s_nop 4
	global_atomic_add v193, v2, s[6:7]
.LBB0_397:
	s_or_b64 exec, exec, s[8:9]
	s_add_i32 s2, s100, 1
	v_mul_lo_u32 v2, v0, s2
	s_mov_b64 s[6:7], exec
	v_readlane_b32 s8, v253, 24
	v_readlane_b32 s9, v253, 25
	s_mov_b64 s[10:11], 0
	s_nop 3
	global_load_dword v0, v193, s[8:9] sc1
	s_waitcnt vmcnt(0)
	v_cmp_lt_u32_e32 vcc, v0, v2
	s_and_saveexec_b64 s[8:9], vcc
	s_cbranch_execz .LBB0_408
	s_mov_b32 s2, 1
	s_branch .LBB0_401

; __device__ __forceinline__ unsigned xb_ld(unsigned* p)              { return __hip_atomic_load(p, __ATOMIC_RELAXED, __HIP_MEMORY_SCOPE_AGENT); }
; #define XB_SPIN(cond, bar) do { unsigned _sp = 0; while (cond) { __builtin_amdgcn_s_sleep(1); \
;     if ((++_sp & 255u) == 0u) { if (xb_ld(&(bar)[XB_TMO])) break; if (_sp > XB_SPIN_CAP) { atomicAdd(&(bar)[XB_TMO], 1u); break; } } } } while (0)
; __device__ __forceinline__ void xcd_barrier(const XcdBarrier& b) {
;     ...
;             else XB_SPIN(xb_ld(&bar[XB_TOPGEN]) == tg, bar);
.LBB0_405:
	v_readlane_b32 s14, v253, 24
	v_readlane_b32 s15, v253, 25
	s_add_i32 s2, s2, 1
	s_mov_b64 s[16:17], -1
	s_nop 2
	global_load_dword v0, v193, s[14:15] sc1
	s_waitcnt vmcnt(0)
	v_cmp_ge_u32_e32 vcc, v0, v2
	s_orn2_b64 s[14:15], vcc, exec
	s_branch .LBB0_400

; __device__ __forceinline__ unsigned xb_add(unsigned* p, unsigned v) { return __hip_atomic_fetch_add(p, v, __ATOMIC_RELAXED, __HIP_MEMORY_SCOPE_AGENT); }
; __device__ __forceinline__ void xcd_barrier(const XcdBarrier& b) {
;     ...
;             xb_add(&bar[XB_XGEN(b.x)], 1u);
;             asm volatile("s_waitcnt vmcnt(0)" ::: "memory");
.Lxl_release:
	s_mov_b64 s[6:7], exec
	v_mbcnt_lo_u32_b32 v0, s6, 0
	v_mbcnt_hi_u32_b32 v0, s7, v0
	v_cmp_eq_u32_e32 vcc, 0, v0
	s_waitcnt vmcnt(0)
	s_and_saveexec_b64 s[8:9], vcc
	s_cbranch_execz .LBB0_8
	s_bcnt1_i32_b64 s2, s[6:7]
	v_readlane_b32 s6, v253, 22
	v_mov_b32_e32 v0, s2
	v_readlane_b32 s7, v253, 23
	s_nop 4
	s_branch .LBB0_8
